# diff fast block: ALiBi base computed straight into its accumulator register (copy removed), V-slot LDS address kept across even->odd step
# speedup vs baseline: 1.0025x; 1.0025x over previous
.Ldf_fast:
	s_add_i32 s0, s43, 2
	s_waitcnt vmcnt(4) lgkmcnt(0)
	s_barrier
	s_add_i32 s20, s58, s43
	s_cmp_lt_i32 s20, s89
	v_mfma_f32_32x32x16_bf16 v[2:17], v[158:161], v[182:185], v[2:17]
	v_subrev_u32_e32 v198, 64, v197
	s_cselect_b64 s[26:27], -1, 0
	v_cvt_f32_i32_e32 v98, v198
	v_cndmask_b32_e64 v188, -v193, v193, s[26:27]
	v_add_u32_e32 v199, s15, v240
	ds_read_b64_tr_b16 v[200:201], v199 offset:51200
	ds_read_b64_tr_b16 v[202:203], v199 offset:51712
	v_fma_f32 v114, v188, v98, -v233
	v_exp_f32_e32 v66, v66
	v_exp_f32_e32 v67, v67
	v_fmamk_f32 v98, v188, 0x42000000, v114
	v_add_f32_e32 v115, v188, v114
	v_mfma_f32_32x32x16_bf16 v[2:17], v[154:157], v[178:181], v[2:17]
	ds_read_b64_tr_b16 v[182:183], v199 offset:52224
	ds_read_b64_tr_b16 v[184:185], v199 offset:52736
	v_fmamk_f32 v99, v188, 0x42040000, v114
	v_fma_f32 v116, 2.0, v188, v114
	v_exp_f32_e32 v68, v68
	v_exp_f32_e32 v69, v69
	s_waitcnt lgkmcnt(2)
	v_mfma_f32_32x32x16_bf16 v[2:17], v[150:153], v[200:203], v[2:17]
	ds_read_b64_tr_b16 v[178:179], v199 offset:53248
	ds_read_b64_tr_b16 v[180:181], v199 offset:53760
	v_add_f32_e32 v187, v187, v66
	v_fmamk_f32 v100, v188, 0x42080000, v114
	v_fmamk_f32 v117, v188, 0x40400000, v114
	v_cvt_pk_bf16_f32 v174, v66, v67
	v_add_f32_e32 v187, v67, v187
	v_exp_f32_e32 v70, v70
	s_waitcnt lgkmcnt(2)
	v_mfma_f32_32x32x16_bf16 v[2:17], v[146:149], v[182:185], v[2:17]
	ds_read_b64_tr_b16 v[200:201], v199 offset:54272
	ds_read_b64_tr_b16 v[202:203], v199 offset:54784
	v_fma_f32 v101, v188, s16, v114
	v_fma_f32 v102, v188, s17, v114
	v_fmamk_f32 v118, v188, 0x41000000, v114
	v_exp_f32_e32 v71, v71
	v_add_f32_e32 v187, v187, v68
	s_waitcnt lgkmcnt(2)
	v_mfma_f32_32x32x16_bf16 v[18:33], v[158:161], v[178:181], v[18:33]
	ds_read_b64_tr_b16 v[182:183], v199 offset:55296
	ds_read_b64_tr_b16 v[184:185], v199 offset:55808
	v_fmamk_f32 v119, v188, 0x41100000, v114
	v_fmamk_f32 v103, v188, 0x42240000, v114
	v_cvt_pk_bf16_f32 v175, v68, v69
	v_add_f32_e32 v187, v187, v69
	v_exp_f32_e32 v72, v72
	s_waitcnt lgkmcnt(2)
	v_mfma_f32_32x32x16_bf16 v[18:33], v[154:157], v[200:203], v[18:33]
	ds_read_b64_tr_b16 v[178:179], v199 offset:56320
	ds_read_b64_tr_b16 v[180:181], v199 offset:56832
	v_fmamk_f32 v120, v188, 0x41200000, v114
	v_fmamk_f32 v104, v188, 0x42280000, v114
	v_exp_f32_e32 v73, v73
	v_add_f32_e32 v187, v187, v70
	v_cvt_pk_bf16_f32 v176, v70, v71
	s_waitcnt lgkmcnt(2)
	v_mfma_f32_32x32x16_bf16 v[18:33], v[150:153], v[182:185], v[18:33]
	ds_read_b64_tr_b16 v[200:201], v199 offset:57344
	ds_read_b64_tr_b16 v[202:203], v199 offset:57856
	v_fmamk_f32 v121, v188, 0x41300000, v114
	v_fmamk_f32 v105, v188, 0x422c0000, v114
	v_add_f32_e32 v182, v187, v71
	v_exp_f32_e32 v74, v74
	v_exp_f32_e32 v75, v75
	s_waitcnt lgkmcnt(2)
	v_mfma_f32_32x32x16_bf16 v[18:33], v[146:149], v[178:181], v[18:33]
	ds_read_b64_tr_b16 v[204:205], v199 offset:58368
	ds_read_b64_tr_b16 v[206:207], v199 offset:58880
	v_add_f32_e32 v178, v182, v72
	v_fmamk_f32 v106, v188, 0x42400000, v114
	v_fma_f32 v122, v188, s48, v114
	v_fma_f32 v123, v188, s49, v114
	v_cvt_pk_bf16_f32 v177, v72, v73
	v_add_f32_e32 v187, v73, v178
	s_waitcnt lgkmcnt(2)
	v_mfma_f32_32x32x16_bf16 v[34:49], v[158:161], v[200:203], v[34:49]
	ds_read_b64_tr_b16 v[182:183], v199 offset:59392
	ds_read_b64_tr_b16 v[184:185], v199 offset:59904
	v_fmamk_f32 v107, v188, 0x42440000, v114
	v_fmamk_f32 v124, v188, 0x41900000, v114
	v_exp_f32_e32 v76, v76
	v_exp_f32_e32 v77, v77
	s_waitcnt lgkmcnt(2)
	v_mfma_f32_32x32x16_bf16 v[34:49], v[154:157], v[204:207], v[34:49]
	ds_read_b64_tr_b16 v[178:179], v199 offset:60416
	ds_read_b64_tr_b16 v[180:181], v199 offset:60928
	v_add_f32_e32 v187, v187, v74
	v_fmamk_f32 v108, v188, 0x42480000, v114
	v_fmamk_f32 v125, v188, 0x41980000, v114
	v_cvt_pk_bf16_f32 v170, v74, v75
	v_add_f32_e32 v200, v75, v187
	v_exp_f32_e32 v78, v78
	s_add_u32 s6, s76, s62
	s_addc_u32 s7, s77, s63
	s_add_u32 s26, s6, 0x30000
	s_addc_u32 s27, s7, 0
	s_add_u32 s6, s78, s62
	s_addc_u32 s7, s79, s63
	s_add_u32 s70, s6, 0x30000
	s_addc_u32 s71, s7, 0
	s_add_i32 s6, 0, s59
	s_add_i32 s7, s81, s90
	s_add_u32 s84, s26, 0x8000
	s_addc_u32 s85, s27, 0
	s_add_i32 s15, s6, 0x2000
	s_mov_b32 m0, s6
	s_nop 0
	global_load_lds_dwordx4 v191, s[26:27]
	s_mov_b32 m0, s15
	s_nop 0
	global_load_lds_dwordx4 v191, s[84:85]
	s_mov_b32 m0, s21
	s_add_u32 s26, s70, 0x80
	s_addc_u32 s27, s71, 0
	s_add_i32 s6, s7, 0x2000
	s_mov_b32 m0, s7
	s_nop 0
	global_load_lds_dwordx4 v192, s[70:71]
	s_mov_b32 m0, s6
	s_nop 0
	global_load_lds_dwordx4 v192, s[26:27]
	s_mov_b32 m0, s15
	s_waitcnt lgkmcnt(2)
	v_mfma_f32_32x32x16_bf16 v[34:49], v[150:153], v[182:185], v[34:49]
	ds_read_b64_tr_b16 v[202:203], v199 offset:61440
	ds_read_b64_tr_b16 v[204:205], v199 offset:61952
	v_fma_f32 v109, v188, s56, v114
	v_fma_f32 v110, v188, s57, v114
	v_fmamk_f32 v126, v188, 0x41c00000, v114
	v_exp_f32_e32 v79, v79
	v_add_f32_e32 v187, v200, v76
	s_waitcnt lgkmcnt(2)
	v_mfma_f32_32x32x16_bf16 v[34:49], v[146:149], v[178:181], v[34:49]
	ds_read_b64_tr_b16 v[182:183], v199 offset:62464
	ds_read_b64_tr_b16 v[184:185], v199 offset:62976
	v_fmamk_f32 v127, v188, 0x41c80000, v114
	v_fmamk_f32 v111, v188, 0x42640000, v114
	v_cvt_pk_bf16_f32 v171, v76, v77
	v_add_f32_e32 v187, v187, v77
	v_exp_f32_e32 v80, v80
	s_waitcnt lgkmcnt(2)
	v_mfma_f32_32x32x16_bf16 v[50:65], v[158:161], v[202:205], v[50:65]
	ds_read_b64_tr_b16 v[178:179], v199 offset:63488
	ds_read_b64_tr_b16 v[180:181], v199 offset:64000
	v_fmamk_f32 v128, v188, 0x41d00000, v114
	v_fmamk_f32 v112, v188, 0x42680000, v114
	v_exp_f32_e32 v81, v81
	v_add_f32_e32 v187, v187, v78
	v_cvt_pk_bf16_f32 v172, v78, v79
	s_waitcnt lgkmcnt(2)
	v_mfma_f32_32x32x16_bf16 v[50:65], v[154:157], v[182:185], v[50:65]
	ds_read_b64_tr_b16 v[200:201], v199 offset:64512
	ds_read_b64_tr_b16 v[202:203], v199 offset:65024
	v_fmamk_f32 v129, v188, 0x41d80000, v114
	v_fmamk_f32 v113, v188, 0x426c0000, v114
	v_exp_f32_e32 v82, v82
	v_exp_f32_e32 v83, v83
	v_add_f32_e32 v186, v187, v79
	s_waitcnt lgkmcnt(2)
	v_mfma_f32_32x32x16_bf16 v[50:65], v[150:153], v[178:181], v[50:65]
	ds_read_b128 v[182:185], v190 offset:16384
	v_add_f32_e32 v178, v186, v80
	v_cvt_pk_bf16_f32 v173, v80, v81
	v_add_f32_e32 v186, v81, v178
	v_exp_f32_e32 v84, v84
	v_exp_f32_e32 v85, v85
	s_waitcnt lgkmcnt(1)
	v_mfma_f32_32x32x16_bf16 v[50:65], v[146:149], v[200:203], v[50:65]
	ds_read_b128 v[178:181], v190 offset:24576
	v_add_f32_e32 v186, v186, v82
	v_cvt_pk_bf16_f32 v166, v82, v83
	v_add_f32_e32 v199, v83, v186
	v_exp_f32_e32 v86, v86
	v_exp_f32_e32 v87, v87
	s_waitcnt lgkmcnt(1)
	v_mfma_f32_32x32x16_bf16 v[114:129], v[182:185], v[130:133], v[114:129]
	ds_read_b128 v[186:189], v194 offset:16384
	v_add_f32_e32 v182, v199, v84
	v_cvt_pk_bf16_f32 v167, v84, v85
	v_add_f32_e32 v199, v85, v182
	v_exp_f32_e32 v88, v88
	v_exp_f32_e32 v89, v89
	s_waitcnt lgkmcnt(1)
	v_mfma_f32_32x32x16_bf16 v[98:113], v[178:181], v[130:133], v[98:113]
	ds_read_b128 v[182:185], v194 offset:24576
	v_add_f32_e32 v178, v199, v86
	v_cvt_pk_bf16_f32 v168, v86, v87
	v_add_f32_e32 v199, v87, v178
	v_exp_f32_e32 v90, v90
	v_exp_f32_e32 v91, v91
	s_waitcnt lgkmcnt(1)
	v_mfma_f32_32x32x16_bf16 v[114:129], v[186:189], v[134:137], v[114:129]
	ds_read_b128 v[178:181], v195 offset:16384
	v_add_f32_e32 v186, v199, v88
	v_cvt_pk_bf16_f32 v169, v88, v89
	v_add_f32_e32 v199, v89, v186
	v_exp_f32_e32 v92, v92
	v_exp_f32_e32 v93, v93
	s_waitcnt lgkmcnt(1)
	v_mfma_f32_32x32x16_bf16 v[98:113], v[182:185], v[134:137], v[98:113]
	ds_read_b128 v[186:189], v195 offset:24576
	v_add_f32_e32 v182, v199, v90
	v_cvt_pk_bf16_f32 v162, v90, v91
	v_add_f32_e32 v182, v91, v182
	v_exp_f32_e32 v94, v94
	v_exp_f32_e32 v95, v95
	s_waitcnt lgkmcnt(1)
	v_mfma_f32_32x32x16_bf16 v[114:129], v[178:181], v[138:141], v[114:129]
	ds_read_b128 v[200:203], v196 offset:16384
	v_add_f32_e32 v178, v182, v92
	v_cvt_pk_bf16_f32 v163, v92, v93
	v_add_f32_e32 v178, v93, v178
	v_exp_f32_e32 v96, v96
	v_exp_f32_e32 v97, v97
	s_waitcnt lgkmcnt(1)
	v_mfma_f32_32x32x16_bf16 v[98:113], v[186:189], v[138:141], v[98:113]
	ds_read_b128 v[204:207], v196 offset:24576
	v_add_f32_e32 v165, v178, v94
	v_add_f32_e32 v165, v95, v165
	v_add_f32_e32 v178, v96, v165
	v_cvt_pk_bf16_f32 v164, v94, v95
	v_cvt_pk_bf16_f32 v165, v96, v97
	v_add_f32_e32 v187, v97, v178
	s_waitcnt lgkmcnt(1)
	v_mfma_f32_32x32x16_bf16 v[114:129], v[200:203], v[142:145], v[114:129]
	v_add_u32_e32 v199, s80, v240
	ds_read_b64_tr_b16 v[182:183], v199 offset:49152
	ds_read_b64_tr_b16 v[184:185], v199 offset:49664
	s_waitcnt lgkmcnt(2)
	v_mfma_f32_32x32x16_bf16 v[98:113], v[204:207], v[142:145], v[98:113]
	ds_read_b64_tr_b16 v[178:179], v199 offset:50176
	ds_read_b64_tr_b16 v[180:181], v199 offset:50688
	s_waitcnt vmcnt(4) lgkmcnt(0)
	s_barrier
	s_add_i32 s6, s81, 0x4000
	s_cmp_lg_u32 s81, 0x10000
	s_cselect_b32 s21, s6, 0
	s_add_i32 s20, s20, 1
	s_cmp_lt_i32 s20, s89
	v_mfma_f32_32x32x16_bf16 v[2:17], v[174:177], v[182:185], v[2:17]
	s_cselect_b64 s[6:7], -1, 0
	v_cvt_f32_i32_e32 v66, v197
	v_cndmask_b32_e64 v188, -v193, v193, s[6:7]
	ds_read_b64_tr_b16 v[200:201], v199 offset:51200
	ds_read_b64_tr_b16 v[202:203], v199 offset:51712
	v_fma_f32 v66, v188, v66, -v233
	v_exp_f32_e32 v114, v114
	v_exp_f32_e32 v115, v115
	v_fmamk_f32 v82, v188, 0x42000000, v66
	v_add_f32_e32 v67, v188, v66
	v_mfma_f32_32x32x16_bf16 v[2:17], v[170:173], v[178:181], v[2:17]
	ds_read_b64_tr_b16 v[182:183], v199 offset:52224
	ds_read_b64_tr_b16 v[184:185], v199 offset:52736
	v_fmamk_f32 v83, v188, 0x42040000, v66
	v_fma_f32 v68, 2.0, v188, v66
	v_exp_f32_e32 v116, v116
	v_exp_f32_e32 v117, v117
	s_waitcnt lgkmcnt(2)
	v_mfma_f32_32x32x16_bf16 v[2:17], v[166:169], v[200:203], v[2:17]
	ds_read_b64_tr_b16 v[178:179], v199 offset:53248
	ds_read_b64_tr_b16 v[180:181], v199 offset:53760
	v_add_f32_e32 v187, v187, v114
	v_fmamk_f32 v84, v188, 0x42080000, v66
	v_fmamk_f32 v69, v188, 0x40400000, v66
	v_cvt_pk_bf16_f32 v158, v114, v115
	v_add_f32_e32 v187, v115, v187
	v_exp_f32_e32 v118, v118
	s_waitcnt lgkmcnt(2)
	v_mfma_f32_32x32x16_bf16 v[2:17], v[162:165], v[182:185], v[2:17]
	ds_read_b64_tr_b16 v[200:201], v199 offset:54272
	ds_read_b64_tr_b16 v[202:203], v199 offset:54784
	v_fma_f32 v85, v188, s16, v66
	v_fma_f32 v86, v188, s17, v66
	v_fmamk_f32 v70, v188, 0x41000000, v66
	v_exp_f32_e32 v119, v119
	v_add_f32_e32 v187, v187, v116
	s_waitcnt lgkmcnt(2)
	v_mfma_f32_32x32x16_bf16 v[18:33], v[174:177], v[178:181], v[18:33]
	ds_read_b64_tr_b16 v[182:183], v199 offset:55296
	ds_read_b64_tr_b16 v[184:185], v199 offset:55808
	v_fmamk_f32 v71, v188, 0x41100000, v66
	v_fmamk_f32 v87, v188, 0x42240000, v66
	v_cvt_pk_bf16_f32 v159, v116, v117
	v_add_f32_e32 v187, v187, v117
	v_exp_f32_e32 v120, v120
	s_waitcnt lgkmcnt(2)
	v_mfma_f32_32x32x16_bf16 v[18:33], v[170:173], v[200:203], v[18:33]
	ds_read_b64_tr_b16 v[178:179], v199 offset:56320
	ds_read_b64_tr_b16 v[180:181], v199 offset:56832
	v_fmamk_f32 v72, v188, 0x41200000, v66
	v_fmamk_f32 v88, v188, 0x42280000, v66
	v_exp_f32_e32 v121, v121
	v_add_f32_e32 v187, v187, v118
	v_cvt_pk_bf16_f32 v160, v118, v119
	s_waitcnt lgkmcnt(2)
	v_mfma_f32_32x32x16_bf16 v[18:33], v[166:169], v[182:185], v[18:33]
	ds_read_b64_tr_b16 v[200:201], v199 offset:57344
	ds_read_b64_tr_b16 v[202:203], v199 offset:57856
	v_fmamk_f32 v73, v188, 0x41300000, v66
	v_fmamk_f32 v89, v188, 0x422c0000, v66
	v_add_f32_e32 v182, v187, v119
	v_exp_f32_e32 v122, v122
	v_exp_f32_e32 v123, v123
	s_waitcnt lgkmcnt(2)
	v_mfma_f32_32x32x16_bf16 v[18:33], v[162:165], v[178:181], v[18:33]
	ds_read_b64_tr_b16 v[204:205], v199 offset:58368
	ds_read_b64_tr_b16 v[206:207], v199 offset:58880
	v_add_f32_e32 v178, v182, v120
	v_fmamk_f32 v90, v188, 0x42400000, v66
	v_fma_f32 v74, v188, s48, v66
	v_fma_f32 v75, v188, s49, v66
	v_cvt_pk_bf16_f32 v161, v120, v121
	v_add_f32_e32 v187, v121, v178
	s_waitcnt lgkmcnt(2)
	v_mfma_f32_32x32x16_bf16 v[34:49], v[174:177], v[200:203], v[34:49]
	ds_read_b64_tr_b16 v[182:183], v199 offset:59392
	ds_read_b64_tr_b16 v[184:185], v199 offset:59904
	v_fmamk_f32 v91, v188, 0x42440000, v66
	v_fmamk_f32 v76, v188, 0x41900000, v66
	v_exp_f32_e32 v124, v124
	v_exp_f32_e32 v125, v125
	s_waitcnt lgkmcnt(2)
	v_mfma_f32_32x32x16_bf16 v[34:49], v[170:173], v[204:207], v[34:49]
	ds_read_b64_tr_b16 v[178:179], v199 offset:60416
	ds_read_b64_tr_b16 v[180:181], v199 offset:60928
	v_add_f32_e32 v187, v187, v122
	v_fmamk_f32 v92, v188, 0x42480000, v66
	v_fmamk_f32 v77, v188, 0x41980000, v66
	v_cvt_pk_bf16_f32 v154, v122, v123
	v_add_f32_e32 v198, v123, v187
	v_exp_f32_e32 v126, v126
	s_add_u32 s6, s76, s62
	s_addc_u32 s7, s77, s63
	s_add_u32 s6, s6, 0x40000
	s_addc_u32 s7, s7, 0
	s_add_u32 s15, s78, s62
	s_addc_u32 s20, s79, s63
	s_add_u32 s24, s15, 0x40000
	s_addc_u32 s25, s20, 0
	s_add_i32 s15, 0x4000, s59
	s_add_i32 s20, s21, s90
	s_add_u32 s26, s6, 0x8000
	s_addc_u32 s27, s7, 0
	s_add_i32 s68, s15, 0x2000
	s_mov_b32 m0, s15
	s_nop 0
	global_load_lds_dwordx4 v191, s[6:7]
	s_mov_b32 m0, s68
	s_nop 0
	global_load_lds_dwordx4 v191, s[26:27]
	s_mov_b32 m0, s69
	s_add_u32 s6, s24, 0x80
	s_addc_u32 s7, s25, 0
	s_add_i32 s15, s20, 0x2000
	s_mov_b32 m0, s20
	s_nop 0
	global_load_lds_dwordx4 v192, s[24:25]
	s_mov_b32 m0, s15
	s_nop 0
	global_load_lds_dwordx4 v192, s[6:7]
	s_mov_b32 m0, s26
	s_waitcnt lgkmcnt(2)
	v_mfma_f32_32x32x16_bf16 v[34:49], v[166:169], v[182:185], v[34:49]
	ds_read_b64_tr_b16 v[200:201], v199 offset:61440
	ds_read_b64_tr_b16 v[202:203], v199 offset:61952
	s_add_i32 s6, s80, 0x4000
	s_cmp_lg_u32 s80, 0x10000
	v_fma_f32 v93, v188, s56, v66
	v_fma_f32 v94, v188, s57, v66
	s_cselect_b32 s15, s6, 0
	v_fmamk_f32 v78, v188, 0x41c00000, v66
	v_exp_f32_e32 v127, v127
	v_add_f32_e32 v187, v198, v124
	s_waitcnt lgkmcnt(2)
	v_mfma_f32_32x32x16_bf16 v[34:49], v[162:165], v[178:181], v[34:49]
	ds_read_b64_tr_b16 v[182:183], v199 offset:62464
	ds_read_b64_tr_b16 v[184:185], v199 offset:62976
	v_fmamk_f32 v79, v188, 0x41c80000, v66
	v_fmamk_f32 v95, v188, 0x42640000, v66
	v_cvt_pk_bf16_f32 v155, v124, v125
	v_add_f32_e32 v187, v187, v125
	v_exp_f32_e32 v128, v128
	s_waitcnt lgkmcnt(2)
	v_mfma_f32_32x32x16_bf16 v[50:65], v[174:177], v[200:203], v[50:65]
	ds_read_b64_tr_b16 v[178:179], v199 offset:63488
	ds_read_b64_tr_b16 v[180:181], v199 offset:64000
	v_fmamk_f32 v80, v188, 0x41d00000, v66
	v_fmamk_f32 v96, v188, 0x42680000, v66
	v_exp_f32_e32 v129, v129
	v_add_f32_e32 v187, v187, v126
	v_cvt_pk_bf16_f32 v156, v126, v127
	s_waitcnt lgkmcnt(2)
	v_mfma_f32_32x32x16_bf16 v[50:65], v[170:173], v[182:185], v[50:65]
	ds_read_b64_tr_b16 v[200:201], v199 offset:64512
	ds_read_b64_tr_b16 v[202:203], v199 offset:65024
	v_fmamk_f32 v81, v188, 0x41d80000, v66
	v_fmamk_f32 v97, v188, 0x426c0000, v66
	v_exp_f32_e32 v98, v98
	v_exp_f32_e32 v99, v99
	v_add_f32_e32 v186, v187, v127
	s_waitcnt lgkmcnt(2)
	v_mfma_f32_32x32x16_bf16 v[50:65], v[166:169], v[178:181], v[50:65]
	ds_read_b128 v[182:185], v190 offset:32768
	v_add_f32_e32 v178, v186, v128
	v_cvt_pk_bf16_f32 v157, v128, v129
	v_add_f32_e32 v186, v129, v178
	v_exp_f32_e32 v100, v100
	v_exp_f32_e32 v101, v101
	s_waitcnt lgkmcnt(1)
	v_mfma_f32_32x32x16_bf16 v[50:65], v[162:165], v[200:203], v[50:65]
	ds_read_b128 v[178:181], v190 offset:40960
	v_add_f32_e32 v186, v186, v98
	v_cvt_pk_bf16_f32 v150, v98, v99
	v_add_f32_e32 v198, v99, v186
	v_exp_f32_e32 v102, v102
	v_exp_f32_e32 v103, v103
	s_waitcnt lgkmcnt(1)
	v_mfma_f32_32x32x16_bf16 v[66:81], v[182:185], v[130:133], v[66:81]
	ds_read_b128 v[186:189], v194 offset:32768
	v_add_f32_e32 v182, v198, v100
	v_cvt_pk_bf16_f32 v151, v100, v101
	v_add_f32_e32 v198, v101, v182
	v_exp_f32_e32 v104, v104
	v_exp_f32_e32 v105, v105
	s_waitcnt lgkmcnt(1)
	v_mfma_f32_32x32x16_bf16 v[82:97], v[178:181], v[130:133], v[82:97]
	ds_read_b128 v[182:185], v194 offset:40960
	v_add_f32_e32 v178, v198, v102
	v_cvt_pk_bf16_f32 v152, v102, v103
	v_add_f32_e32 v198, v103, v178
	v_exp_f32_e32 v106, v106
	v_exp_f32_e32 v107, v107
	s_waitcnt lgkmcnt(1)
	v_mfma_f32_32x32x16_bf16 v[66:81], v[186:189], v[134:137], v[66:81]
	ds_read_b128 v[178:181], v195 offset:32768
	v_add_f32_e32 v186, v198, v104
	v_cvt_pk_bf16_f32 v153, v104, v105
	v_add_f32_e32 v198, v105, v186
	v_exp_f32_e32 v108, v108
	v_exp_f32_e32 v109, v109
	s_waitcnt lgkmcnt(1)
	v_mfma_f32_32x32x16_bf16 v[82:97], v[182:185], v[134:137], v[82:97]
	ds_read_b128 v[186:189], v195 offset:40960
	v_add_f32_e32 v182, v198, v106
	v_cvt_pk_bf16_f32 v146, v106, v107
	v_add_f32_e32 v182, v107, v182
	v_exp_f32_e32 v110, v110
	v_exp_f32_e32 v111, v111
	s_waitcnt lgkmcnt(1)
	v_mfma_f32_32x32x16_bf16 v[66:81], v[178:181], v[138:141], v[66:81]
	ds_read_b128 v[198:201], v196 offset:32768
	v_add_f32_e32 v178, v182, v108
	v_cvt_pk_bf16_f32 v147, v108, v109
	v_add_f32_e32 v178, v109, v178
	v_exp_f32_e32 v112, v112
	v_exp_f32_e32 v113, v113
	s_waitcnt lgkmcnt(1)
	v_mfma_f32_32x32x16_bf16 v[82:97], v[186:189], v[138:141], v[82:97]
	ds_read_b128 v[202:205], v196 offset:40960
	v_add_f32_e32 v149, v178, v110
	v_add_f32_e32 v149, v111, v149
	v_add_f32_e32 v178, v112, v149
	v_cvt_pk_bf16_f32 v148, v110, v111
	v_cvt_pk_bf16_f32 v149, v112, v113
	v_add_f32_e32 v187, v113, v178
	s_waitcnt lgkmcnt(1)
	v_mfma_f32_32x32x16_bf16 v[66:81], v[198:201], v[142:145], v[66:81]
	v_add_u32_e32 v199, s15, v240
	ds_read_b64_tr_b16 v[182:183], v199 offset:49152
	ds_read_b64_tr_b16 v[184:185], v199 offset:49664
	s_waitcnt lgkmcnt(2)
	v_mfma_f32_32x32x16_bf16 v[82:97], v[202:205], v[142:145], v[82:97]
	ds_read_b64_tr_b16 v[178:179], v199 offset:50176
	ds_read_b64_tr_b16 v[180:181], v199 offset:50688
	s_add_i32 s6, s15, 0x4000
	s_cmp_lg_u32 s15, 0x10000
	s_cselect_b32 s80, s6, 0
	s_add_i32 s6, s21, 0x4000
	s_cmp_lg_u32 s21, 0x10000
	s_cselect_b32 s81, s6, 0
	s_add_u32 s78, s78, 0x20000
	s_addc_u32 s79, s79, 0
	s_add_u32 s76, s76, 0x20000
	s_addc_u32 s77, s77, 0
	v_add_u32_e32 v197, 0x80, v197
	s_mov_b32 s43, s0
	s_add_i32 s0, s43, 2
	s_waitcnt vmcnt(4) lgkmcnt(0)
	s_barrier
	s_add_i32 s20, s58, s43
	s_cmp_lt_i32 s20, s89
	v_mfma_f32_32x32x16_bf16 v[2:17], v[158:161], v[182:185], v[2:17]
	v_subrev_u32_e32 v198, 64, v197
	s_cselect_b64 s[26:27], -1, 0
	v_cvt_f32_i32_e32 v98, v198
	v_cndmask_b32_e64 v188, -v193, v193, s[26:27]
	ds_read_b64_tr_b16 v[200:201], v199 offset:51200
	ds_read_b64_tr_b16 v[202:203], v199 offset:51712
	v_fma_f32 v114, v188, v98, -v233
	v_exp_f32_e32 v66, v66
	v_exp_f32_e32 v67, v67
	v_fmamk_f32 v98, v188, 0x42000000, v114
	v_add_f32_e32 v115, v188, v114
	v_mfma_f32_32x32x16_bf16 v[2:17], v[154:157], v[178:181], v[2:17]
	ds_read_b64_tr_b16 v[182:183], v199 offset:52224
	ds_read_b64_tr_b16 v[184:185], v199 offset:52736
	v_fmamk_f32 v99, v188, 0x42040000, v114
	v_fma_f32 v116, 2.0, v188, v114
	v_exp_f32_e32 v68, v68
	v_exp_f32_e32 v69, v69
	s_waitcnt lgkmcnt(2)
	v_mfma_f32_32x32x16_bf16 v[2:17], v[150:153], v[200:203], v[2:17]
	ds_read_b64_tr_b16 v[178:179], v199 offset:53248
	ds_read_b64_tr_b16 v[180:181], v199 offset:53760
	v_add_f32_e32 v187, v187, v66
	v_fmamk_f32 v100, v188, 0x42080000, v114
	v_fmamk_f32 v117, v188, 0x40400000, v114
	v_cvt_pk_bf16_f32 v174, v66, v67
	v_add_f32_e32 v187, v67, v187
	v_exp_f32_e32 v70, v70
	s_waitcnt lgkmcnt(2)
	v_mfma_f32_32x32x16_bf16 v[2:17], v[146:149], v[182:185], v[2:17]
	ds_read_b64_tr_b16 v[200:201], v199 offset:54272
	ds_read_b64_tr_b16 v[202:203], v199 offset:54784
	v_fma_f32 v101, v188, s16, v114
	v_fma_f32 v102, v188, s17, v114
	v_fmamk_f32 v118, v188, 0x41000000, v114
	v_exp_f32_e32 v71, v71
	v_add_f32_e32 v187, v187, v68
	s_waitcnt lgkmcnt(2)
	v_mfma_f32_32x32x16_bf16 v[18:33], v[158:161], v[178:181], v[18:33]
	ds_read_b64_tr_b16 v[182:183], v199 offset:55296
	ds_read_b64_tr_b16 v[184:185], v199 offset:55808
	v_fmamk_f32 v119, v188, 0x41100000, v114
	v_fmamk_f32 v103, v188, 0x42240000, v114
	v_cvt_pk_bf16_f32 v175, v68, v69
	v_add_f32_e32 v187, v187, v69
	v_exp_f32_e32 v72, v72
	s_waitcnt lgkmcnt(2)
	v_mfma_f32_32x32x16_bf16 v[18:33], v[154:157], v[200:203], v[18:33]
	ds_read_b64_tr_b16 v[178:179], v199 offset:56320
	ds_read_b64_tr_b16 v[180:181], v199 offset:56832
	v_fmamk_f32 v120, v188, 0x41200000, v114
	v_fmamk_f32 v104, v188, 0x42280000, v114
	v_exp_f32_e32 v73, v73
	v_add_f32_e32 v187, v187, v70
	v_cvt_pk_bf16_f32 v176, v70, v71
	s_waitcnt lgkmcnt(2)
	v_mfma_f32_32x32x16_bf16 v[18:33], v[150:153], v[182:185], v[18:33]
	ds_read_b64_tr_b16 v[200:201], v199 offset:57344
	ds_read_b64_tr_b16 v[202:203], v199 offset:57856
	v_fmamk_f32 v121, v188, 0x41300000, v114
	v_fmamk_f32 v105, v188, 0x422c0000, v114
	v_add_f32_e32 v182, v187, v71
	v_exp_f32_e32 v74, v74
	v_exp_f32_e32 v75, v75
	s_waitcnt lgkmcnt(2)
	v_mfma_f32_32x32x16_bf16 v[18:33], v[146:149], v[178:181], v[18:33]
	ds_read_b64_tr_b16 v[204:205], v199 offset:58368
	ds_read_b64_tr_b16 v[206:207], v199 offset:58880
	v_add_f32_e32 v178, v182, v72
	v_fmamk_f32 v106, v188, 0x42400000, v114
	v_fma_f32 v122, v188, s48, v114
	v_fma_f32 v123, v188, s49, v114
	v_cvt_pk_bf16_f32 v177, v72, v73
	v_add_f32_e32 v187, v73, v178
	s_waitcnt lgkmcnt(2)
	v_mfma_f32_32x32x16_bf16 v[34:49], v[158:161], v[200:203], v[34:49]
	ds_read_b64_tr_b16 v[182:183], v199 offset:59392
	ds_read_b64_tr_b16 v[184:185], v199 offset:59904
	v_fmamk_f32 v107, v188, 0x42440000, v114
	v_fmamk_f32 v124, v188, 0x41900000, v114
	v_exp_f32_e32 v76, v76
	v_exp_f32_e32 v77, v77
	s_waitcnt lgkmcnt(2)
	v_mfma_f32_32x32x16_bf16 v[34:49], v[154:157], v[204:207], v[34:49]
	ds_read_b64_tr_b16 v[178:179], v199 offset:60416
	ds_read_b64_tr_b16 v[180:181], v199 offset:60928
	v_add_f32_e32 v187, v187, v74
	v_fmamk_f32 v108, v188, 0x42480000, v114
	v_fmamk_f32 v125, v188, 0x41980000, v114
	v_cvt_pk_bf16_f32 v170, v74, v75
	v_add_f32_e32 v200, v75, v187
	v_exp_f32_e32 v78, v78
	s_add_u32 s6, s76, s62
	s_addc_u32 s7, s77, s63
	s_add_u32 s26, s6, 0x30000
	s_addc_u32 s27, s7, 0
	s_add_u32 s6, s78, s62
	s_addc_u32 s7, s79, s63
	s_add_u32 s70, s6, 0x30000
	s_addc_u32 s71, s7, 0
	s_add_i32 s6, 0x8000, s59
	s_add_i32 s7, s81, s90
	s_add_u32 s84, s26, 0x8000
	s_addc_u32 s85, s27, 0
	s_add_i32 s15, s6, 0x2000
	s_mov_b32 m0, s6
	s_nop 0
	global_load_lds_dwordx4 v191, s[26:27]
	s_mov_b32 m0, s15
	s_nop 0
	global_load_lds_dwordx4 v191, s[84:85]
	s_mov_b32 m0, s21
	s_add_u32 s26, s70, 0x80
	s_addc_u32 s27, s71, 0
	s_add_i32 s6, s7, 0x2000
	s_mov_b32 m0, s7
	s_nop 0
	global_load_lds_dwordx4 v192, s[70:71]
	s_mov_b32 m0, s6
	s_nop 0
	global_load_lds_dwordx4 v192, s[26:27]
	s_mov_b32 m0, s15
	s_waitcnt lgkmcnt(2)
	v_mfma_f32_32x32x16_bf16 v[34:49], v[150:153], v[182:185], v[34:49]
	ds_read_b64_tr_b16 v[202:203], v199 offset:61440
	ds_read_b64_tr_b16 v[204:205], v199 offset:61952
	v_fma_f32 v109, v188, s56, v114
	v_fma_f32 v110, v188, s57, v114
	v_fmamk_f32 v126, v188, 0x41c00000, v114
	v_exp_f32_e32 v79, v79
	v_add_f32_e32 v187, v200, v76
	s_waitcnt lgkmcnt(2)
	v_mfma_f32_32x32x16_bf16 v[34:49], v[146:149], v[178:181], v[34:49]
	ds_read_b64_tr_b16 v[182:183], v199 offset:62464
	ds_read_b64_tr_b16 v[184:185], v199 offset:62976
	v_fmamk_f32 v127, v188, 0x41c80000, v114
	v_fmamk_f32 v111, v188, 0x42640000, v114
	v_cvt_pk_bf16_f32 v171, v76, v77
	v_add_f32_e32 v187, v187, v77
	v_exp_f32_e32 v80, v80
	s_waitcnt lgkmcnt(2)
	v_mfma_f32_32x32x16_bf16 v[50:65], v[158:161], v[202:205], v[50:65]
	ds_read_b64_tr_b16 v[178:179], v199 offset:63488
	ds_read_b64_tr_b16 v[180:181], v199 offset:64000
	v_fmamk_f32 v128, v188, 0x41d00000, v114
	v_fmamk_f32 v112, v188, 0x42680000, v114
	v_exp_f32_e32 v81, v81
	v_add_f32_e32 v187, v187, v78
	v_cvt_pk_bf16_f32 v172, v78, v79
	s_waitcnt lgkmcnt(2)
	v_mfma_f32_32x32x16_bf16 v[50:65], v[154:157], v[182:185], v[50:65]
	ds_read_b64_tr_b16 v[200:201], v199 offset:64512
	ds_read_b64_tr_b16 v[202:203], v199 offset:65024
	v_fmamk_f32 v129, v188, 0x41d80000, v114
	v_fmamk_f32 v113, v188, 0x426c0000, v114
	v_exp_f32_e32 v82, v82
	v_exp_f32_e32 v83, v83
	v_add_f32_e32 v186, v187, v79
	s_waitcnt lgkmcnt(2)
	v_mfma_f32_32x32x16_bf16 v[50:65], v[150:153], v[178:181], v[50:65]
	ds_read_b128 v[182:185], v190
	v_add_f32_e32 v178, v186, v80
	v_cvt_pk_bf16_f32 v173, v80, v81
	v_add_f32_e32 v186, v81, v178
	v_exp_f32_e32 v84, v84
	v_exp_f32_e32 v85, v85
	s_waitcnt lgkmcnt(1)
	v_mfma_f32_32x32x16_bf16 v[50:65], v[146:149], v[200:203], v[50:65]
	ds_read_b128 v[178:181], v190 offset:8192
	v_add_f32_e32 v186, v186, v82
	v_cvt_pk_bf16_f32 v166, v82, v83
	v_add_f32_e32 v199, v83, v186
	v_exp_f32_e32 v86, v86
	v_exp_f32_e32 v87, v87
	s_waitcnt lgkmcnt(1)
	v_mfma_f32_32x32x16_bf16 v[114:129], v[182:185], v[130:133], v[114:129]
	ds_read_b128 v[186:189], v194
	v_add_f32_e32 v182, v199, v84
	v_cvt_pk_bf16_f32 v167, v84, v85
	v_add_f32_e32 v199, v85, v182
	v_exp_f32_e32 v88, v88
	v_exp_f32_e32 v89, v89
	s_waitcnt lgkmcnt(1)
	v_mfma_f32_32x32x16_bf16 v[98:113], v[178:181], v[130:133], v[98:113]
	ds_read_b128 v[182:185], v194 offset:8192
	v_add_f32_e32 v178, v199, v86
	v_cvt_pk_bf16_f32 v168, v86, v87
	v_add_f32_e32 v199, v87, v178
	v_exp_f32_e32 v90, v90
	v_exp_f32_e32 v91, v91
	s_waitcnt lgkmcnt(1)
	v_mfma_f32_32x32x16_bf16 v[114:129], v[186:189], v[134:137], v[114:129]
	ds_read_b128 v[178:181], v195
	v_add_f32_e32 v186, v199, v88
	v_cvt_pk_bf16_f32 v169, v88, v89
	v_add_f32_e32 v199, v89, v186
	v_exp_f32_e32 v92, v92
	v_exp_f32_e32 v93, v93
	s_waitcnt lgkmcnt(1)
	v_mfma_f32_32x32x16_bf16 v[98:113], v[182:185], v[134:137], v[98:113]
	ds_read_b128 v[186:189], v195 offset:8192
	v_add_f32_e32 v182, v199, v90
	v_cvt_pk_bf16_f32 v162, v90, v91
	v_add_f32_e32 v182, v91, v182
	v_exp_f32_e32 v94, v94
	v_exp_f32_e32 v95, v95
	s_waitcnt lgkmcnt(1)
	v_mfma_f32_32x32x16_bf16 v[114:129], v[178:181], v[138:141], v[114:129]
	ds_read_b128 v[200:203], v196
	v_add_f32_e32 v178, v182, v92
	v_cvt_pk_bf16_f32 v163, v92, v93
	v_add_f32_e32 v178, v93, v178
	v_exp_f32_e32 v96, v96
	v_exp_f32_e32 v97, v97
	s_waitcnt lgkmcnt(1)
	v_mfma_f32_32x32x16_bf16 v[98:113], v[186:189], v[138:141], v[98:113]
	ds_read_b128 v[204:207], v196 offset:8192
	v_add_f32_e32 v165, v178, v94
	v_add_f32_e32 v165, v95, v165
	v_add_f32_e32 v178, v96, v165
	v_cvt_pk_bf16_f32 v164, v94, v95
	v_cvt_pk_bf16_f32 v165, v96, v97
	v_add_f32_e32 v187, v97, v178
	s_waitcnt lgkmcnt(1)
	v_mfma_f32_32x32x16_bf16 v[114:129], v[200:203], v[142:145], v[114:129]
	v_add_u32_e32 v199, s80, v240
	ds_read_b64_tr_b16 v[182:183], v199 offset:49152
	ds_read_b64_tr_b16 v[184:185], v199 offset:49664
	s_waitcnt lgkmcnt(2)
	v_mfma_f32_32x32x16_bf16 v[98:113], v[204:207], v[142:145], v[98:113]
	ds_read_b64_tr_b16 v[178:179], v199 offset:50176
	ds_read_b64_tr_b16 v[180:181], v199 offset:50688
	s_waitcnt vmcnt(4) lgkmcnt(0)
	s_barrier
	s_add_i32 s6, s81, 0x4000
	s_cmp_lg_u32 s81, 0x10000
	s_cselect_b32 s21, s6, 0
	s_add_i32 s20, s20, 1
	s_cmp_lt_i32 s20, s89
	v_mfma_f32_32x32x16_bf16 v[2:17], v[174:177], v[182:185], v[2:17]
	s_cselect_b64 s[6:7], -1, 0
	v_cvt_f32_i32_e32 v66, v197
	v_cndmask_b32_e64 v188, -v193, v193, s[6:7]
	ds_read_b64_tr_b16 v[200:201], v199 offset:51200
	ds_read_b64_tr_b16 v[202:203], v199 offset:51712
	v_fma_f32 v66, v188, v66, -v233
	v_exp_f32_e32 v114, v114
	v_exp_f32_e32 v115, v115
	v_fmamk_f32 v82, v188, 0x42000000, v66
	v_add_f32_e32 v67, v188, v66
	v_mfma_f32_32x32x16_bf16 v[2:17], v[170:173], v[178:181], v[2:17]
	ds_read_b64_tr_b16 v[182:183], v199 offset:52224
	ds_read_b64_tr_b16 v[184:185], v199 offset:52736
	v_fmamk_f32 v83, v188, 0x42040000, v66
	v_fma_f32 v68, 2.0, v188, v66
	v_exp_f32_e32 v116, v116
	v_exp_f32_e32 v117, v117
	s_waitcnt lgkmcnt(2)
	v_mfma_f32_32x32x16_bf16 v[2:17], v[166:169], v[200:203], v[2:17]
	ds_read_b64_tr_b16 v[178:179], v199 offset:53248
	ds_read_b64_tr_b16 v[180:181], v199 offset:53760
	v_add_f32_e32 v187, v187, v114
	v_fmamk_f32 v84, v188, 0x42080000, v66
	v_fmamk_f32 v69, v188, 0x40400000, v66
	v_cvt_pk_bf16_f32 v158, v114, v115
	v_add_f32_e32 v187, v115, v187
	v_exp_f32_e32 v118, v118
	s_waitcnt lgkmcnt(2)
	v_mfma_f32_32x32x16_bf16 v[2:17], v[162:165], v[182:185], v[2:17]
	ds_read_b64_tr_b16 v[200:201], v199 offset:54272
	ds_read_b64_tr_b16 v[202:203], v199 offset:54784
	v_fma_f32 v85, v188, s16, v66
	v_fma_f32 v86, v188, s17, v66
	v_fmamk_f32 v70, v188, 0x41000000, v66
	v_exp_f32_e32 v119, v119
	v_add_f32_e32 v187, v187, v116
	s_waitcnt lgkmcnt(2)
	v_mfma_f32_32x32x16_bf16 v[18:33], v[174:177], v[178:181], v[18:33]
	ds_read_b64_tr_b16 v[182:183], v199 offset:55296
	ds_read_b64_tr_b16 v[184:185], v199 offset:55808
	v_fmamk_f32 v71, v188, 0x41100000, v66
	v_fmamk_f32 v87, v188, 0x42240000, v66
	v_cvt_pk_bf16_f32 v159, v116, v117
	v_add_f32_e32 v187, v187, v117
	v_exp_f32_e32 v120, v120
	s_waitcnt lgkmcnt(2)
	v_mfma_f32_32x32x16_bf16 v[18:33], v[170:173], v[200:203], v[18:33]
	ds_read_b64_tr_b16 v[178:179], v199 offset:56320
	ds_read_b64_tr_b16 v[180:181], v199 offset:56832
	v_fmamk_f32 v72, v188, 0x41200000, v66
	v_fmamk_f32 v88, v188, 0x42280000, v66
	v_exp_f32_e32 v121, v121
	v_add_f32_e32 v187, v187, v118
	v_cvt_pk_bf16_f32 v160, v118, v119
	s_waitcnt lgkmcnt(2)
	v_mfma_f32_32x32x16_bf16 v[18:33], v[166:169], v[182:185], v[18:33]
	ds_read_b64_tr_b16 v[200:201], v199 offset:57344
	ds_read_b64_tr_b16 v[202:203], v199 offset:57856
	v_fmamk_f32 v73, v188, 0x41300000, v66
	v_fmamk_f32 v89, v188, 0x422c0000, v66
	v_add_f32_e32 v182, v187, v119
	v_exp_f32_e32 v122, v122
	v_exp_f32_e32 v123, v123
	s_waitcnt lgkmcnt(2)
	v_mfma_f32_32x32x16_bf16 v[18:33], v[162:165], v[178:181], v[18:33]
	ds_read_b64_tr_b16 v[204:205], v199 offset:58368
	ds_read_b64_tr_b16 v[206:207], v199 offset:58880
	v_add_f32_e32 v178, v182, v120
	v_fmamk_f32 v90, v188, 0x42400000, v66
	v_fma_f32 v74, v188, s48, v66
	v_fma_f32 v75, v188, s49, v66
	v_cvt_pk_bf16_f32 v161, v120, v121
	v_add_f32_e32 v187, v121, v178
	s_waitcnt lgkmcnt(2)
	v_mfma_f32_32x32x16_bf16 v[34:49], v[174:177], v[200:203], v[34:49]
	ds_read_b64_tr_b16 v[182:183], v199 offset:59392
	ds_read_b64_tr_b16 v[184:185], v199 offset:59904
	v_fmamk_f32 v91, v188, 0x42440000, v66
	v_fmamk_f32 v76, v188, 0x41900000, v66
	v_exp_f32_e32 v124, v124
	v_exp_f32_e32 v125, v125
	s_waitcnt lgkmcnt(2)
	v_mfma_f32_32x32x16_bf16 v[34:49], v[170:173], v[204:207], v[34:49]
	ds_read_b64_tr_b16 v[178:179], v199 offset:60416
	ds_read_b64_tr_b16 v[180:181], v199 offset:60928
	v_add_f32_e32 v187, v187, v122
	v_fmamk_f32 v92, v188, 0x42480000, v66
	v_fmamk_f32 v77, v188, 0x41980000, v66
	v_cvt_pk_bf16_f32 v154, v122, v123
	v_add_f32_e32 v198, v123, v187
	v_exp_f32_e32 v126, v126
	s_add_u32 s6, s76, s62
	s_addc_u32 s7, s77, s63
	s_add_u32 s6, s6, 0x40000
	s_addc_u32 s7, s7, 0
	s_add_u32 s15, s78, s62
	s_addc_u32 s20, s79, s63
	s_add_u32 s24, s15, 0x40000
	s_addc_u32 s25, s20, 0
	s_add_i32 s15, 0, s59
	s_add_i32 s20, s21, s90
	s_add_u32 s26, s6, 0x8000
	s_addc_u32 s27, s7, 0
	s_add_i32 s68, s15, 0x2000
	s_mov_b32 m0, s15
	s_nop 0
	global_load_lds_dwordx4 v191, s[6:7]
	s_mov_b32 m0, s68
	s_nop 0
	global_load_lds_dwordx4 v191, s[26:27]
	s_mov_b32 m0, s69
	s_add_u32 s6, s24, 0x80
	s_addc_u32 s7, s25, 0
	s_add_i32 s15, s20, 0x2000
	s_mov_b32 m0, s20
	s_nop 0
	global_load_lds_dwordx4 v192, s[24:25]
	s_mov_b32 m0, s15
	s_nop 0
	global_load_lds_dwordx4 v192, s[6:7]
	s_mov_b32 m0, s26
	s_waitcnt lgkmcnt(2)
	v_mfma_f32_32x32x16_bf16 v[34:49], v[166:169], v[182:185], v[34:49]
	ds_read_b64_tr_b16 v[200:201], v199 offset:61440
	ds_read_b64_tr_b16 v[202:203], v199 offset:61952
	s_add_i32 s6, s80, 0x4000
	s_cmp_lg_u32 s80, 0x10000
	v_fma_f32 v93, v188, s56, v66
	v_fma_f32 v94, v188, s57, v66
	s_cselect_b32 s15, s6, 0
	v_fmamk_f32 v78, v188, 0x41c00000, v66
	v_exp_f32_e32 v127, v127
	v_add_f32_e32 v187, v198, v124
	s_waitcnt lgkmcnt(2)
	v_mfma_f32_32x32x16_bf16 v[34:49], v[162:165], v[178:181], v[34:49]
	ds_read_b64_tr_b16 v[182:183], v199 offset:62464
	ds_read_b64_tr_b16 v[184:185], v199 offset:62976
	v_fmamk_f32 v79, v188, 0x41c80000, v66
	v_fmamk_f32 v95, v188, 0x42640000, v66
	v_cvt_pk_bf16_f32 v155, v124, v125
	v_add_f32_e32 v187, v187, v125
	v_exp_f32_e32 v128, v128
	s_waitcnt lgkmcnt(2)
	v_mfma_f32_32x32x16_bf16 v[50:65], v[174:177], v[200:203], v[50:65]
	ds_read_b64_tr_b16 v[178:179], v199 offset:63488
	ds_read_b64_tr_b16 v[180:181], v199 offset:64000
	v_fmamk_f32 v80, v188, 0x41d00000, v66
	v_fmamk_f32 v96, v188, 0x42680000, v66
	v_exp_f32_e32 v129, v129
	v_add_f32_e32 v187, v187, v126
	v_cvt_pk_bf16_f32 v156, v126, v127
	s_waitcnt lgkmcnt(2)
	v_mfma_f32_32x32x16_bf16 v[50:65], v[170:173], v[182:185], v[50:65]
	ds_read_b64_tr_b16 v[200:201], v199 offset:64512
	ds_read_b64_tr_b16 v[202:203], v199 offset:65024
	v_fmamk_f32 v81, v188, 0x41d80000, v66
	v_fmamk_f32 v97, v188, 0x426c0000, v66
	v_exp_f32_e32 v98, v98
	v_exp_f32_e32 v99, v99
	v_add_f32_e32 v186, v187, v127
	s_waitcnt lgkmcnt(2)
	v_mfma_f32_32x32x16_bf16 v[50:65], v[166:169], v[178:181], v[50:65]
	ds_read_b128 v[182:185], v190 offset:16384
	v_add_f32_e32 v178, v186, v128
	v_cvt_pk_bf16_f32 v157, v128, v129
	v_add_f32_e32 v186, v129, v178
	v_exp_f32_e32 v100, v100
	v_exp_f32_e32 v101, v101
	s_waitcnt lgkmcnt(1)
	v_mfma_f32_32x32x16_bf16 v[50:65], v[162:165], v[200:203], v[50:65]
	ds_read_b128 v[178:181], v190 offset:24576
	v_add_f32_e32 v186, v186, v98
	v_cvt_pk_bf16_f32 v150, v98, v99
	v_add_f32_e32 v198, v99, v186
	v_exp_f32_e32 v102, v102
	v_exp_f32_e32 v103, v103
	s_waitcnt lgkmcnt(1)
	v_mfma_f32_32x32x16_bf16 v[66:81], v[182:185], v[130:133], v[66:81]
	ds_read_b128 v[186:189], v194 offset:16384
	v_add_f32_e32 v182, v198, v100
	v_cvt_pk_bf16_f32 v151, v100, v101
	v_add_f32_e32 v198, v101, v182
	v_exp_f32_e32 v104, v104
	v_exp_f32_e32 v105, v105
	s_waitcnt lgkmcnt(1)
	v_mfma_f32_32x32x16_bf16 v[82:97], v[178:181], v[130:133], v[82:97]
	ds_read_b128 v[182:185], v194 offset:24576
	v_add_f32_e32 v178, v198, v102
	v_cvt_pk_bf16_f32 v152, v102, v103
	v_add_f32_e32 v198, v103, v178
	v_exp_f32_e32 v106, v106
	v_exp_f32_e32 v107, v107
	s_waitcnt lgkmcnt(1)
	v_mfma_f32_32x32x16_bf16 v[66:81], v[186:189], v[134:137], v[66:81]
	ds_read_b128 v[178:181], v195 offset:16384
	v_add_f32_e32 v186, v198, v104
	v_cvt_pk_bf16_f32 v153, v104, v105
	v_add_f32_e32 v198, v105, v186
	v_exp_f32_e32 v108, v108
	v_exp_f32_e32 v109, v109
	s_waitcnt lgkmcnt(1)
	v_mfma_f32_32x32x16_bf16 v[82:97], v[182:185], v[134:137], v[82:97]
	ds_read_b128 v[186:189], v195 offset:24576
	v_add_f32_e32 v182, v198, v106
	v_cvt_pk_bf16_f32 v146, v106, v107
	v_add_f32_e32 v182, v107, v182
	v_exp_f32_e32 v110, v110
	v_exp_f32_e32 v111, v111
	s_waitcnt lgkmcnt(1)
	v_mfma_f32_32x32x16_bf16 v[66:81], v[178:181], v[138:141], v[66:81]
	ds_read_b128 v[198:201], v196 offset:16384
	v_add_f32_e32 v178, v182, v108
	v_cvt_pk_bf16_f32 v147, v108, v109
	v_add_f32_e32 v178, v109, v178
	v_exp_f32_e32 v112, v112
	v_exp_f32_e32 v113, v113
	s_waitcnt lgkmcnt(1)
	v_mfma_f32_32x32x16_bf16 v[82:97], v[186:189], v[138:141], v[82:97]
	ds_read_b128 v[202:205], v196 offset:24576
	v_add_f32_e32 v149, v178, v110
	v_add_f32_e32 v149, v111, v149
	v_add_f32_e32 v178, v112, v149
	v_cvt_pk_bf16_f32 v148, v110, v111
	v_cvt_pk_bf16_f32 v149, v112, v113
	v_add_f32_e32 v187, v113, v178
	s_waitcnt lgkmcnt(1)
	v_mfma_f32_32x32x16_bf16 v[66:81], v[198:201], v[142:145], v[66:81]
	v_add_u32_e32 v199, s15, v240
	ds_read_b64_tr_b16 v[182:183], v199 offset:49152
	ds_read_b64_tr_b16 v[184:185], v199 offset:49664
	s_waitcnt lgkmcnt(2)
	v_mfma_f32_32x32x16_bf16 v[82:97], v[202:205], v[142:145], v[82:97]
	ds_read_b64_tr_b16 v[178:179], v199 offset:50176
	ds_read_b64_tr_b16 v[180:181], v199 offset:50688
	s_add_i32 s6, s15, 0x4000
	s_cmp_lg_u32 s15, 0x10000
	s_cselect_b32 s80, s6, 0
	s_add_i32 s6, s21, 0x4000
	s_cmp_lg_u32 s21, 0x10000
	s_cselect_b32 s81, s6, 0
	s_add_u32 s78, s78, 0x20000
	s_addc_u32 s79, s79, 0
	s_add_u32 s76, s76, 0x20000
	s_addc_u32 s77, s77, 0
	v_add_u32_e32 v197, 0x80, v197
	s_mov_b32 s43, s0
	s_add_i32 s0, s43, 2
	s_waitcnt vmcnt(4) lgkmcnt(0)
	s_barrier
	s_add_i32 s20, s58, s43
	s_cmp_lt_i32 s20, s89
	v_mfma_f32_32x32x16_bf16 v[2:17], v[158:161], v[182:185], v[2:17]
	v_subrev_u32_e32 v198, 64, v197
	s_cselect_b64 s[26:27], -1, 0
	v_cvt_f32_i32_e32 v98, v198
	v_cndmask_b32_e64 v188, -v193, v193, s[26:27]
	ds_read_b64_tr_b16 v[200:201], v199 offset:51200
	ds_read_b64_tr_b16 v[202:203], v199 offset:51712
	v_fma_f32 v114, v188, v98, -v233
	v_exp_f32_e32 v66, v66
	v_exp_f32_e32 v67, v67
	v_fmamk_f32 v98, v188, 0x42000000, v114
	v_add_f32_e32 v115, v188, v114
	v_mfma_f32_32x32x16_bf16 v[2:17], v[154:157], v[178:181], v[2:17]
	ds_read_b64_tr_b16 v[182:183], v199 offset:52224
	ds_read_b64_tr_b16 v[184:185], v199 offset:52736
	v_fmamk_f32 v99, v188, 0x42040000, v114
	v_fma_f32 v116, 2.0, v188, v114
	v_exp_f32_e32 v68, v68
	v_exp_f32_e32 v69, v69
	s_waitcnt lgkmcnt(2)
	v_mfma_f32_32x32x16_bf16 v[2:17], v[150:153], v[200:203], v[2:17]
	ds_read_b64_tr_b16 v[178:179], v199 offset:53248
	ds_read_b64_tr_b16 v[180:181], v199 offset:53760
	v_add_f32_e32 v187, v187, v66
	v_fmamk_f32 v100, v188, 0x42080000, v114
	v_fmamk_f32 v117, v188, 0x40400000, v114
	v_cvt_pk_bf16_f32 v174, v66, v67
	v_add_f32_e32 v187, v67, v187
	v_exp_f32_e32 v70, v70
	s_waitcnt lgkmcnt(2)
	v_mfma_f32_32x32x16_bf16 v[2:17], v[146:149], v[182:185], v[2:17]
	ds_read_b64_tr_b16 v[200:201], v199 offset:54272
	ds_read_b64_tr_b16 v[202:203], v199 offset:54784
	v_fma_f32 v101, v188, s16, v114
	v_fma_f32 v102, v188, s17, v114
	v_fmamk_f32 v118, v188, 0x41000000, v114
	v_exp_f32_e32 v71, v71
	v_add_f32_e32 v187, v187, v68
	s_waitcnt lgkmcnt(2)
	v_mfma_f32_32x32x16_bf16 v[18:33], v[158:161], v[178:181], v[18:33]
	ds_read_b64_tr_b16 v[182:183], v199 offset:55296
	ds_read_b64_tr_b16 v[184:185], v199 offset:55808
	v_fmamk_f32 v119, v188, 0x41100000, v114
	v_fmamk_f32 v103, v188, 0x42240000, v114
	v_cvt_pk_bf16_f32 v175, v68, v69
	v_add_f32_e32 v187, v187, v69
	v_exp_f32_e32 v72, v72
	s_waitcnt lgkmcnt(2)
	v_mfma_f32_32x32x16_bf16 v[18:33], v[154:157], v[200:203], v[18:33]
	ds_read_b64_tr_b16 v[178:179], v199 offset:56320
	ds_read_b64_tr_b16 v[180:181], v199 offset:56832
	v_fmamk_f32 v120, v188, 0x41200000, v114
	v_fmamk_f32 v104, v188, 0x42280000, v114
	v_exp_f32_e32 v73, v73
	v_add_f32_e32 v187, v187, v70
	v_cvt_pk_bf16_f32 v176, v70, v71
	s_waitcnt lgkmcnt(2)
	v_mfma_f32_32x32x16_bf16 v[18:33], v[150:153], v[182:185], v[18:33]
	ds_read_b64_tr_b16 v[200:201], v199 offset:57344
	ds_read_b64_tr_b16 v[202:203], v199 offset:57856
	v_fmamk_f32 v121, v188, 0x41300000, v114
	v_fmamk_f32 v105, v188, 0x422c0000, v114
	v_add_f32_e32 v182, v187, v71
	v_exp_f32_e32 v74, v74
	v_exp_f32_e32 v75, v75
	s_waitcnt lgkmcnt(2)
	v_mfma_f32_32x32x16_bf16 v[18:33], v[146:149], v[178:181], v[18:33]
	ds_read_b64_tr_b16 v[204:205], v199 offset:58368
	ds_read_b64_tr_b16 v[206:207], v199 offset:58880
	v_add_f32_e32 v178, v182, v72
	v_fmamk_f32 v106, v188, 0x42400000, v114
	v_fma_f32 v122, v188, s48, v114
	v_fma_f32 v123, v188, s49, v114
	v_cvt_pk_bf16_f32 v177, v72, v73
	v_add_f32_e32 v187, v73, v178
	s_waitcnt lgkmcnt(2)
	v_mfma_f32_32x32x16_bf16 v[34:49], v[158:161], v[200:203], v[34:49]
	ds_read_b64_tr_b16 v[182:183], v199 offset:59392
	ds_read_b64_tr_b16 v[184:185], v199 offset:59904
	v_fmamk_f32 v107, v188, 0x42440000, v114
	v_fmamk_f32 v124, v188, 0x41900000, v114
	v_exp_f32_e32 v76, v76
	v_exp_f32_e32 v77, v77
	s_waitcnt lgkmcnt(2)
	v_mfma_f32_32x32x16_bf16 v[34:49], v[154:157], v[204:207], v[34:49]
	ds_read_b64_tr_b16 v[178:179], v199 offset:60416
	ds_read_b64_tr_b16 v[180:181], v199 offset:60928
	v_add_f32_e32 v187, v187, v74
	v_fmamk_f32 v108, v188, 0x42480000, v114
	v_fmamk_f32 v125, v188, 0x41980000, v114
	v_cvt_pk_bf16_f32 v170, v74, v75
	v_add_f32_e32 v200, v75, v187
	v_exp_f32_e32 v78, v78
	s_add_u32 s6, s76, s62
	s_addc_u32 s7, s77, s63
	s_add_u32 s26, s6, 0x30000
	s_addc_u32 s27, s7, 0
	s_add_u32 s6, s78, s62
	s_addc_u32 s7, s79, s63
	s_add_u32 s70, s6, 0x30000
	s_addc_u32 s71, s7, 0
	s_add_i32 s6, 0x4000, s59
	s_add_i32 s7, s81, s90
	s_add_u32 s84, s26, 0x8000
	s_addc_u32 s85, s27, 0
	s_add_i32 s15, s6, 0x2000
	s_mov_b32 m0, s6
	s_nop 0
	global_load_lds_dwordx4 v191, s[26:27]
	s_mov_b32 m0, s15
	s_nop 0
	global_load_lds_dwordx4 v191, s[84:85]
	s_mov_b32 m0, s21
	s_add_u32 s26, s70, 0x80
	s_addc_u32 s27, s71, 0
	s_add_i32 s6, s7, 0x2000
	s_mov_b32 m0, s7
	s_nop 0
	global_load_lds_dwordx4 v192, s[70:71]
	s_mov_b32 m0, s6
	s_nop 0
	global_load_lds_dwordx4 v192, s[26:27]
	s_mov_b32 m0, s15
	s_waitcnt lgkmcnt(2)
	v_mfma_f32_32x32x16_bf16 v[34:49], v[150:153], v[182:185], v[34:49]
	ds_read_b64_tr_b16 v[202:203], v199 offset:61440
	ds_read_b64_tr_b16 v[204:205], v199 offset:61952
	v_fma_f32 v109, v188, s56, v114
	v_fma_f32 v110, v188, s57, v114
	v_fmamk_f32 v126, v188, 0x41c00000, v114
	v_exp_f32_e32 v79, v79
	v_add_f32_e32 v187, v200, v76
	s_waitcnt lgkmcnt(2)
	v_mfma_f32_32x32x16_bf16 v[34:49], v[146:149], v[178:181], v[34:49]
	ds_read_b64_tr_b16 v[182:183], v199 offset:62464
	ds_read_b64_tr_b16 v[184:185], v199 offset:62976
	v_fmamk_f32 v127, v188, 0x41c80000, v114
	v_fmamk_f32 v111, v188, 0x42640000, v114
	v_cvt_pk_bf16_f32 v171, v76, v77
	v_add_f32_e32 v187, v187, v77
	v_exp_f32_e32 v80, v80
	s_waitcnt lgkmcnt(2)
	v_mfma_f32_32x32x16_bf16 v[50:65], v[158:161], v[202:205], v[50:65]
	ds_read_b64_tr_b16 v[178:179], v199 offset:63488
	ds_read_b64_tr_b16 v[180:181], v199 offset:64000
	v_fmamk_f32 v128, v188, 0x41d00000, v114
	v_fmamk_f32 v112, v188, 0x42680000, v114
	v_exp_f32_e32 v81, v81
	v_add_f32_e32 v187, v187, v78
	v_cvt_pk_bf16_f32 v172, v78, v79
	s_waitcnt lgkmcnt(2)
	v_mfma_f32_32x32x16_bf16 v[50:65], v[154:157], v[182:185], v[50:65]
	ds_read_b64_tr_b16 v[200:201], v199 offset:64512
	ds_read_b64_tr_b16 v[202:203], v199 offset:65024
	v_fmamk_f32 v129, v188, 0x41d80000, v114
	v_fmamk_f32 v113, v188, 0x426c0000, v114
	v_exp_f32_e32 v82, v82
	v_exp_f32_e32 v83, v83
	v_add_f32_e32 v186, v187, v79
	s_waitcnt lgkmcnt(2)
	v_mfma_f32_32x32x16_bf16 v[50:65], v[150:153], v[178:181], v[50:65]
	ds_read_b128 v[182:185], v190 offset:32768
	v_add_f32_e32 v178, v186, v80
	v_cvt_pk_bf16_f32 v173, v80, v81
	v_add_f32_e32 v186, v81, v178
	v_exp_f32_e32 v84, v84
	v_exp_f32_e32 v85, v85
	s_waitcnt lgkmcnt(1)
	v_mfma_f32_32x32x16_bf16 v[50:65], v[146:149], v[200:203], v[50:65]
	ds_read_b128 v[178:181], v190 offset:40960
	v_add_f32_e32 v186, v186, v82
	v_cvt_pk_bf16_f32 v166, v82, v83
	v_add_f32_e32 v199, v83, v186
	v_exp_f32_e32 v86, v86
	v_exp_f32_e32 v87, v87
	s_waitcnt lgkmcnt(1)
	v_mfma_f32_32x32x16_bf16 v[114:129], v[182:185], v[130:133], v[114:129]
	ds_read_b128 v[186:189], v194 offset:32768
	v_add_f32_e32 v182, v199, v84
	v_cvt_pk_bf16_f32 v167, v84, v85
	v_add_f32_e32 v199, v85, v182
	v_exp_f32_e32 v88, v88
	v_exp_f32_e32 v89, v89
	s_waitcnt lgkmcnt(1)
	v_mfma_f32_32x32x16_bf16 v[98:113], v[178:181], v[130:133], v[98:113]
	ds_read_b128 v[182:185], v194 offset:40960
	v_add_f32_e32 v178, v199, v86
	v_cvt_pk_bf16_f32 v168, v86, v87
	v_add_f32_e32 v199, v87, v178
	v_exp_f32_e32 v90, v90
	v_exp_f32_e32 v91, v91
	s_waitcnt lgkmcnt(1)
	v_mfma_f32_32x32x16_bf16 v[114:129], v[186:189], v[134:137], v[114:129]
	ds_read_b128 v[178:181], v195 offset:32768
	v_add_f32_e32 v186, v199, v88
	v_cvt_pk_bf16_f32 v169, v88, v89
	v_add_f32_e32 v199, v89, v186
	v_exp_f32_e32 v92, v92
	v_exp_f32_e32 v93, v93
	s_waitcnt lgkmcnt(1)
	v_mfma_f32_32x32x16_bf16 v[98:113], v[182:185], v[134:137], v[98:113]
	ds_read_b128 v[186:189], v195 offset:40960
	v_add_f32_e32 v182, v199, v90
	v_cvt_pk_bf16_f32 v162, v90, v91
	v_add_f32_e32 v182, v91, v182
	v_exp_f32_e32 v94, v94
	v_exp_f32_e32 v95, v95
	s_waitcnt lgkmcnt(1)
	v_mfma_f32_32x32x16_bf16 v[114:129], v[178:181], v[138:141], v[114:129]
	ds_read_b128 v[200:203], v196 offset:32768
	v_add_f32_e32 v178, v182, v92
	v_cvt_pk_bf16_f32 v163, v92, v93
	v_add_f32_e32 v178, v93, v178
	v_exp_f32_e32 v96, v96
	v_exp_f32_e32 v97, v97
	s_waitcnt lgkmcnt(1)
	v_mfma_f32_32x32x16_bf16 v[98:113], v[186:189], v[138:141], v[98:113]
	ds_read_b128 v[204:207], v196 offset:40960
	v_add_f32_e32 v165, v178, v94
	v_add_f32_e32 v165, v95, v165
	v_add_f32_e32 v178, v96, v165
	v_cvt_pk_bf16_f32 v164, v94, v95
	v_cvt_pk_bf16_f32 v165, v96, v97
	v_add_f32_e32 v187, v97, v178
	s_waitcnt lgkmcnt(1)
	v_mfma_f32_32x32x16_bf16 v[114:129], v[200:203], v[142:145], v[114:129]
	v_add_u32_e32 v199, s80, v240
	ds_read_b64_tr_b16 v[182:183], v199 offset:49152
	ds_read_b64_tr_b16 v[184:185], v199 offset:49664
	s_waitcnt lgkmcnt(2)
	v_mfma_f32_32x32x16_bf16 v[98:113], v[204:207], v[142:145], v[98:113]
	ds_read_b64_tr_b16 v[178:179], v199 offset:50176
	ds_read_b64_tr_b16 v[180:181], v199 offset:50688
	s_waitcnt vmcnt(4) lgkmcnt(0)
	s_barrier
	s_add_i32 s6, s81, 0x4000
	s_cmp_lg_u32 s81, 0x10000
	s_cselect_b32 s21, s6, 0
	s_add_i32 s20, s20, 1
	s_cmp_lt_i32 s20, s89
	v_mfma_f32_32x32x16_bf16 v[2:17], v[174:177], v[182:185], v[2:17]
	s_cselect_b64 s[6:7], -1, 0
	v_cvt_f32_i32_e32 v66, v197
	v_cndmask_b32_e64 v188, -v193, v193, s[6:7]
	ds_read_b64_tr_b16 v[200:201], v199 offset:51200
	ds_read_b64_tr_b16 v[202:203], v199 offset:51712
	v_fma_f32 v66, v188, v66, -v233
	v_exp_f32_e32 v114, v114
	v_exp_f32_e32 v115, v115
	v_fmamk_f32 v82, v188, 0x42000000, v66
	v_add_f32_e32 v67, v188, v66
	v_mfma_f32_32x32x16_bf16 v[2:17], v[170:173], v[178:181], v[2:17]
	ds_read_b64_tr_b16 v[182:183], v199 offset:52224
	ds_read_b64_tr_b16 v[184:185], v199 offset:52736
	v_fmamk_f32 v83, v188, 0x42040000, v66
	v_fma_f32 v68, 2.0, v188, v66
	v_exp_f32_e32 v116, v116
	v_exp_f32_e32 v117, v117
	s_waitcnt lgkmcnt(2)
	v_mfma_f32_32x32x16_bf16 v[2:17], v[166:169], v[200:203], v[2:17]
	ds_read_b64_tr_b16 v[178:179], v199 offset:53248
	ds_read_b64_tr_b16 v[180:181], v199 offset:53760
	v_add_f32_e32 v187, v187, v114
	v_fmamk_f32 v84, v188, 0x42080000, v66
	v_fmamk_f32 v69, v188, 0x40400000, v66
	v_cvt_pk_bf16_f32 v158, v114, v115
	v_add_f32_e32 v187, v115, v187
	v_exp_f32_e32 v118, v118
	s_waitcnt lgkmcnt(2)
	v_mfma_f32_32x32x16_bf16 v[2:17], v[162:165], v[182:185], v[2:17]
	ds_read_b64_tr_b16 v[200:201], v199 offset:54272
	ds_read_b64_tr_b16 v[202:203], v199 offset:54784
	v_fma_f32 v85, v188, s16, v66
	v_fma_f32 v86, v188, s17, v66
	v_fmamk_f32 v70, v188, 0x41000000, v66
	v_exp_f32_e32 v119, v119
	v_add_f32_e32 v187, v187, v116
	s_waitcnt lgkmcnt(2)
	v_mfma_f32_32x32x16_bf16 v[18:33], v[174:177], v[178:181], v[18:33]
	ds_read_b64_tr_b16 v[182:183], v199 offset:55296
	ds_read_b64_tr_b16 v[184:185], v199 offset:55808
	v_fmamk_f32 v71, v188, 0x41100000, v66
	v_fmamk_f32 v87, v188, 0x42240000, v66
	v_cvt_pk_bf16_f32 v159, v116, v117
	v_add_f32_e32 v187, v187, v117
	v_exp_f32_e32 v120, v120
	s_waitcnt lgkmcnt(2)
	v_mfma_f32_32x32x16_bf16 v[18:33], v[170:173], v[200:203], v[18:33]
	ds_read_b64_tr_b16 v[178:179], v199 offset:56320
	ds_read_b64_tr_b16 v[180:181], v199 offset:56832
	v_fmamk_f32 v72, v188, 0x41200000, v66
	v_fmamk_f32 v88, v188, 0x42280000, v66
	v_exp_f32_e32 v121, v121
	v_add_f32_e32 v187, v187, v118
	v_cvt_pk_bf16_f32 v160, v118, v119
	s_waitcnt lgkmcnt(2)
	v_mfma_f32_32x32x16_bf16 v[18:33], v[166:169], v[182:185], v[18:33]
	ds_read_b64_tr_b16 v[200:201], v199 offset:57344
	ds_read_b64_tr_b16 v[202:203], v199 offset:57856
	v_fmamk_f32 v73, v188, 0x41300000, v66
	v_fmamk_f32 v89, v188, 0x422c0000, v66
	v_add_f32_e32 v182, v187, v119
	v_exp_f32_e32 v122, v122
	v_exp_f32_e32 v123, v123
	s_waitcnt lgkmcnt(2)
	v_mfma_f32_32x32x16_bf16 v[18:33], v[162:165], v[178:181], v[18:33]
	ds_read_b64_tr_b16 v[204:205], v199 offset:58368
	ds_read_b64_tr_b16 v[206:207], v199 offset:58880
	v_add_f32_e32 v178, v182, v120
	v_fmamk_f32 v90, v188, 0x42400000, v66
	v_fma_f32 v74, v188, s48, v66
	v_fma_f32 v75, v188, s49, v66
	v_cvt_pk_bf16_f32 v161, v120, v121
	v_add_f32_e32 v187, v121, v178
	s_waitcnt lgkmcnt(2)
	v_mfma_f32_32x32x16_bf16 v[34:49], v[174:177], v[200:203], v[34:49]
	ds_read_b64_tr_b16 v[182:183], v199 offset:59392
	ds_read_b64_tr_b16 v[184:185], v199 offset:59904
	v_fmamk_f32 v91, v188, 0x42440000, v66
	v_fmamk_f32 v76, v188, 0x41900000, v66
	v_exp_f32_e32 v124, v124
	v_exp_f32_e32 v125, v125
	s_waitcnt lgkmcnt(2)
	v_mfma_f32_32x32x16_bf16 v[34:49], v[170:173], v[204:207], v[34:49]
	ds_read_b64_tr_b16 v[178:179], v199 offset:60416
	ds_read_b64_tr_b16 v[180:181], v199 offset:60928
	v_add_f32_e32 v187, v187, v122
	v_fmamk_f32 v92, v188, 0x42480000, v66
	v_fmamk_f32 v77, v188, 0x41980000, v66
	v_cvt_pk_bf16_f32 v154, v122, v123
	v_add_f32_e32 v198, v123, v187
	v_exp_f32_e32 v126, v126
	s_add_u32 s6, s76, s62
	s_addc_u32 s7, s77, s63
	s_add_u32 s6, s6, 0x40000
	s_addc_u32 s7, s7, 0
	s_add_u32 s15, s78, s62
	s_addc_u32 s20, s79, s63
	s_add_u32 s24, s15, 0x40000
	s_addc_u32 s25, s20, 0
	s_add_i32 s15, 0x8000, s59
	s_add_i32 s20, s21, s90
	s_add_u32 s26, s6, 0x8000
	s_addc_u32 s27, s7, 0
	s_add_i32 s68, s15, 0x2000
	s_mov_b32 m0, s15
	s_nop 0
	global_load_lds_dwordx4 v191, s[6:7]
	s_mov_b32 m0, s68
	s_nop 0
	global_load_lds_dwordx4 v191, s[26:27]
	s_mov_b32 m0, s69
	s_add_u32 s6, s24, 0x80
	s_addc_u32 s7, s25, 0
	s_add_i32 s15, s20, 0x2000
	s_mov_b32 m0, s20
	s_nop 0
	global_load_lds_dwordx4 v192, s[24:25]
	s_mov_b32 m0, s15
	s_nop 0
	global_load_lds_dwordx4 v192, s[6:7]
	s_mov_b32 m0, s26
	s_waitcnt lgkmcnt(2)
	v_mfma_f32_32x32x16_bf16 v[34:49], v[166:169], v[182:185], v[34:49]
	ds_read_b64_tr_b16 v[200:201], v199 offset:61440
	ds_read_b64_tr_b16 v[202:203], v199 offset:61952
	s_add_i32 s6, s80, 0x4000
	s_cmp_lg_u32 s80, 0x10000
	v_fma_f32 v93, v188, s56, v66
	v_fma_f32 v94, v188, s57, v66
	s_cselect_b32 s15, s6, 0
	v_fmamk_f32 v78, v188, 0x41c00000, v66
	v_exp_f32_e32 v127, v127
	v_add_f32_e32 v187, v198, v124
	s_waitcnt lgkmcnt(2)
	v_mfma_f32_32x32x16_bf16 v[34:49], v[162:165], v[178:181], v[34:49]
	ds_read_b64_tr_b16 v[182:183], v199 offset:62464
	ds_read_b64_tr_b16 v[184:185], v199 offset:62976
	v_fmamk_f32 v79, v188, 0x41c80000, v66
	v_fmamk_f32 v95, v188, 0x42640000, v66
	v_cvt_pk_bf16_f32 v155, v124, v125
	v_add_f32_e32 v187, v187, v125
	v_exp_f32_e32 v128, v128
	s_waitcnt lgkmcnt(2)
	v_mfma_f32_32x32x16_bf16 v[50:65], v[174:177], v[200:203], v[50:65]
	ds_read_b64_tr_b16 v[178:179], v199 offset:63488
	ds_read_b64_tr_b16 v[180:181], v199 offset:64000
	v_fmamk_f32 v80, v188, 0x41d00000, v66
	v_fmamk_f32 v96, v188, 0x42680000, v66
	v_exp_f32_e32 v129, v129
	v_add_f32_e32 v187, v187, v126
	v_cvt_pk_bf16_f32 v156, v126, v127
	s_waitcnt lgkmcnt(2)
	v_mfma_f32_32x32x16_bf16 v[50:65], v[170:173], v[182:185], v[50:65]
	ds_read_b64_tr_b16 v[200:201], v199 offset:64512
	ds_read_b64_tr_b16 v[202:203], v199 offset:65024
	v_fmamk_f32 v81, v188, 0x41d80000, v66
	v_fmamk_f32 v97, v188, 0x426c0000, v66
	v_exp_f32_e32 v98, v98
	v_exp_f32_e32 v99, v99
	v_add_f32_e32 v186, v187, v127
	s_waitcnt lgkmcnt(2)
	v_mfma_f32_32x32x16_bf16 v[50:65], v[166:169], v[178:181], v[50:65]
	ds_read_b128 v[182:185], v190
	v_add_f32_e32 v178, v186, v128
	v_cvt_pk_bf16_f32 v157, v128, v129
	v_add_f32_e32 v186, v129, v178
	v_exp_f32_e32 v100, v100
	v_exp_f32_e32 v101, v101
	s_waitcnt lgkmcnt(1)
	v_mfma_f32_32x32x16_bf16 v[50:65], v[162:165], v[200:203], v[50:65]
	ds_read_b128 v[178:181], v190 offset:8192
	v_add_f32_e32 v186, v186, v98
	v_cvt_pk_bf16_f32 v150, v98, v99
	v_add_f32_e32 v198, v99, v186
	v_exp_f32_e32 v102, v102
	v_exp_f32_e32 v103, v103
	s_waitcnt lgkmcnt(1)
	v_mfma_f32_32x32x16_bf16 v[66:81], v[182:185], v[130:133], v[66:81]
	ds_read_b128 v[186:189], v194
	v_add_f32_e32 v182, v198, v100
	v_cvt_pk_bf16_f32 v151, v100, v101
	v_add_f32_e32 v198, v101, v182
	v_exp_f32_e32 v104, v104
	v_exp_f32_e32 v105, v105
	s_waitcnt lgkmcnt(1)
	v_mfma_f32_32x32x16_bf16 v[82:97], v[178:181], v[130:133], v[82:97]
	ds_read_b128 v[182:185], v194 offset:8192
	v_add_f32_e32 v178, v198, v102
	v_cvt_pk_bf16_f32 v152, v102, v103
	v_add_f32_e32 v198, v103, v178
	v_exp_f32_e32 v106, v106
	v_exp_f32_e32 v107, v107
	s_waitcnt lgkmcnt(1)
	v_mfma_f32_32x32x16_bf16 v[66:81], v[186:189], v[134:137], v[66:81]
	ds_read_b128 v[178:181], v195
	v_add_f32_e32 v186, v198, v104
	v_cvt_pk_bf16_f32 v153, v104, v105
	v_add_f32_e32 v198, v105, v186
	v_exp_f32_e32 v108, v108
	v_exp_f32_e32 v109, v109
	s_waitcnt lgkmcnt(1)
	v_mfma_f32_32x32x16_bf16 v[82:97], v[182:185], v[134:137], v[82:97]
	ds_read_b128 v[186:189], v195 offset:8192
	v_add_f32_e32 v182, v198, v106
	v_cvt_pk_bf16_f32 v146, v106, v107
	v_add_f32_e32 v182, v107, v182
	v_exp_f32_e32 v110, v110
	v_exp_f32_e32 v111, v111
	s_waitcnt lgkmcnt(1)
	v_mfma_f32_32x32x16_bf16 v[66:81], v[178:181], v[138:141], v[66:81]
	ds_read_b128 v[198:201], v196
	v_add_f32_e32 v178, v182, v108
	v_cvt_pk_bf16_f32 v147, v108, v109
	v_add_f32_e32 v178, v109, v178
	v_exp_f32_e32 v112, v112
	v_exp_f32_e32 v113, v113
	s_waitcnt lgkmcnt(1)
	v_mfma_f32_32x32x16_bf16 v[82:97], v[186:189], v[138:141], v[82:97]
	ds_read_b128 v[202:205], v196 offset:8192
	v_add_f32_e32 v149, v178, v110
	v_add_f32_e32 v149, v111, v149
	v_add_f32_e32 v178, v112, v149
	v_cvt_pk_bf16_f32 v148, v110, v111
	v_cvt_pk_bf16_f32 v149, v112, v113
	v_add_f32_e32 v187, v113, v178
	s_waitcnt lgkmcnt(1)
	v_mfma_f32_32x32x16_bf16 v[66:81], v[198:201], v[142:145], v[66:81]
	v_add_u32_e32 v180, s15, v240
	ds_read_b64_tr_b16 v[182:183], v180 offset:49152
	ds_read_b64_tr_b16 v[184:185], v180 offset:49664
	s_waitcnt lgkmcnt(2)
	v_mfma_f32_32x32x16_bf16 v[82:97], v[202:205], v[142:145], v[82:97]
	ds_read_b64_tr_b16 v[178:179], v180 offset:50176
	ds_read_b64_tr_b16 v[180:181], v180 offset:50688
	s_add_i32 s6, s15, 0x4000
	s_cmp_lg_u32 s15, 0x10000
	s_cselect_b32 s80, s6, 0
	s_add_i32 s6, s21, 0x4000
	s_cmp_lg_u32 s21, 0x10000
	s_cselect_b32 s81, s6, 0
	s_add_u32 s78, s78, 0x20000
	s_addc_u32 s79, s79, 0
	s_add_u32 s76, s76, 0x20000
	s_addc_u32 s77, s77, 0
	v_add_u32_e32 v197, 0x80, v197
	s_mov_b32 s43, s0
	s_branch .LBB0_1377
